# scan prefetch blocks with compact immediate-offset addressing (4 bases instead of per-row 64-bit address math)
# baseline (speedup 1.0000x reference)
.LBB0_299:
	s_and_b64 s[34:35], s[26:27], exec
	s_brev_b32 s29, 16
	s_cselect_b32 s30, s29, 0xa000000
	s_add_u32 s33, s80, s30
	s_addc_u32 s34, s81, 0
	s_lshl_b32 s94, s2, 9
	s_lshl_b32 s30, s3, 10
	v_lshl_add_u64 v[48:49], v[26:27], 0, s[94:95]
	s_lshl_b32 s94, s31, 1
	s_lshl_b32 s2, s31, 2
	s_add_u32 s2, s33, s2
	s_addc_u32 s3, s34, 0
	v_lshl_add_u64 v[16:17], s[2:3], 0, v[176:177]
	v_mov_b32_e32 v47, v177
	s_mov_b32 s29, 0
	v_lshl_add_u64 v[50:51], v[28:29], 0, s[94:95]
	v_cndmask_b32_e64 v132, v59, v31, s[26:27]
	v_cndmask_b32_e64 v133, v60, v54, s[26:27]
	v_cndmask_b32_e64 v134, v62, v61, s[26:27]
	v_cndmask_b32_e64 v135, v64, v63, s[26:27]
	v_cndmask_b32_e64 v136, v66, v65, s[26:27]
	v_cndmask_b32_e64 v137, v68, v67, s[26:27]
	v_cndmask_b32_e64 v138, v70, v69, s[26:27]
	v_cndmask_b32_e64 v139, v72, v71, s[26:27]
	v_cndmask_b32_e64 v140, v74, v73, s[26:27]
	v_cndmask_b32_e64 v141, v76, v75, s[26:27]
	v_cndmask_b32_e64 v142, v78, v77, s[26:27]
	v_cndmask_b32_e64 v143, v80, v79, s[26:27]
	v_cndmask_b32_e64 v144, v82, v81, s[26:27]
	v_cndmask_b32_e64 v145, v84, v83, s[26:27]
	v_cndmask_b32_e64 v146, v86, v85, s[26:27]
	v_cndmask_b32_e64 v147, v88, v87, s[26:27]
	v_cndmask_b32_e64 v148, v90, v89, s[26:27]
	v_cndmask_b32_e64 v149, v91, v55, s[26:27]
	v_cndmask_b32_e64 v150, v93, v92, s[26:27]
	v_cndmask_b32_e64 v151, v95, v94, s[26:27]
	v_cndmask_b32_e64 v152, v97, v96, s[26:27]
	v_cndmask_b32_e64 v153, v99, v98, s[26:27]
	v_cndmask_b32_e64 v154, v101, v100, s[26:27]
	v_cndmask_b32_e64 v155, v103, v102, s[26:27]
	v_cndmask_b32_e64 v156, v105, v104, s[26:27]
	v_lshl_add_u64 v[52:53], v[16:17], 0, v[46:47]
	v_cndmask_b32_e64 v47, v121, v118, s[26:27]
	v_cndmask_b32_e64 v157, v122, v119, s[26:27]
	v_cndmask_b32_e64 v158, v123, v120, s[26:27]
	s_movk_i32 s31, 0x3c0
	s_movk_i32 s94, 0x7fff
	s_cmp_lg_u64 s[26:27], 0
	s_cselect_b32 s2, s29, s31
	s_add_i32 s2, s2, s30
	v_add_u32_e32 v246, s2, v133
	v_mov_b32_e32 v245, 0
	v_add_u32_e32 v247, s2, v149
	s_cmp_lg_u64 s[26:27], 0
	s_cbranch_scc0 .Lsc_bwd_pre
	v_add_u32_e32 v244, 4, v246
	v_lshlrev_b32_e32 v244, 10, v244
	v_lshl_add_u64 v[236:237], v[244:245], 0, v[48:49]
	v_add_u32_e32 v244, 12, v246
	v_lshlrev_b32_e32 v244, 10, v244
	v_lshl_add_u64 v[238:239], v[244:245], 0, v[48:49]
	v_add_u32_e32 v244, 8, v246
	v_lshlrev_b32_e32 v244, 9, v244
	v_lshl_add_u64 v[240:241], v[244:245], 0, v[44:45]
	v_lshlrev_b32_e32 v244, 9, v247
	v_lshl_add_u64 v[242:243], v[244:245], 0, v[50:51]
	global_load_dword v59, v[236:237], off offset:-4096 sc0 sc1
	global_load_ushort v60, v[240:241], off offset:-4096 sc0 sc1
	global_load_ushort v61, v[240:241], off offset:-3840 sc0 sc1
	global_load_dword v62, v[236:237], off offset:-3072 sc0 sc1
	global_load_ushort v63, v[240:241], off offset:-3584 sc0 sc1
	global_load_ushort v64, v[240:241], off offset:-3328 sc0 sc1
	global_load_dword v65, v[236:237], off offset:-2048 sc0 sc1
	global_load_ushort v66, v[240:241], off offset:-3072 sc0 sc1
	global_load_ushort v67, v[240:241], off offset:-2816 sc0 sc1
	global_load_dword v68, v[236:237], off offset:-1024 sc0 sc1
	global_load_ushort v69, v[240:241], off offset:-2560 sc0 sc1
	global_load_ushort v70, v[240:241], off offset:-2304 sc0 sc1
	global_load_dword v71, v[236:237], off sc0 sc1
	global_load_ushort v72, v[240:241], off offset:-2048 sc0 sc1
	global_load_ushort v73, v[240:241], off offset:-1792 sc0 sc1
	global_load_dword v74, v[236:237], off offset:1024 sc0 sc1
	global_load_ushort v75, v[240:241], off offset:-1536 sc0 sc1
	global_load_ushort v76, v[240:241], off offset:-1280 sc0 sc1
	global_load_dword v77, v[236:237], off offset:2048 sc0 sc1
	global_load_ushort v78, v[240:241], off offset:-1024 sc0 sc1
	global_load_ushort v79, v[240:241], off offset:-768 sc0 sc1
	global_load_dword v80, v[236:237], off offset:3072 sc0 sc1
	global_load_ushort v81, v[240:241], off offset:-512 sc0 sc1
	global_load_ushort v82, v[240:241], off offset:-256 sc0 sc1
	global_load_dword v83, v[238:239], off offset:-4096 sc0 sc1
	global_load_ushort v84, v[240:241], off sc0 sc1
	global_load_ushort v85, v[240:241], off offset:256 sc0 sc1
	global_load_dword v86, v[238:239], off offset:-3072 sc0 sc1
	global_load_ushort v87, v[240:241], off offset:512 sc0 sc1
	global_load_ushort v88, v[240:241], off offset:768 sc0 sc1
	global_load_dword v89, v[238:239], off offset:-2048 sc0 sc1
	global_load_ushort v90, v[240:241], off offset:1024 sc0 sc1
	global_load_ushort v91, v[240:241], off offset:1280 sc0 sc1
	global_load_dword v92, v[238:239], off offset:-1024 sc0 sc1
	global_load_ushort v93, v[240:241], off offset:1536 sc0 sc1
	global_load_ushort v94, v[240:241], off offset:1792 sc0 sc1
	global_load_dword v95, v[238:239], off sc0 sc1
	global_load_ushort v96, v[240:241], off offset:2048 sc0 sc1
	global_load_ushort v97, v[240:241], off offset:2304 sc0 sc1
	global_load_dword v98, v[238:239], off offset:1024 sc0 sc1
	global_load_ushort v99, v[240:241], off offset:2560 sc0 sc1
	global_load_ushort v100, v[240:241], off offset:2816 sc0 sc1
	global_load_dword v101, v[238:239], off offset:2048 sc0 sc1
	global_load_ushort v102, v[240:241], off offset:3072 sc0 sc1
	global_load_ushort v103, v[240:241], off offset:3328 sc0 sc1
	global_load_dword v104, v[238:239], off offset:3072 sc0 sc1
	global_load_ushort v105, v[240:241], off offset:3584 sc0 sc1
	global_load_ushort v227, v[240:241], off offset:3840 sc0 sc1
	global_load_ushort v228, v[242:243], off sc0 sc1
	global_load_ushort v229, v[242:243], off offset:512 sc0 sc1
	global_load_ushort v230, v[242:243], off offset:1024 sc0 sc1
	global_load_ushort v231, v[242:243], off offset:1536 sc0 sc1
	global_load_ushort v232, v[242:243], off offset:2048 sc0 sc1
	global_load_ushort v233, v[242:243], off offset:2560 sc0 sc1
	global_load_ushort v234, v[242:243], off offset:3072 sc0 sc1
	global_load_ushort v235, v[242:243], off offset:3584 sc0 sc1
	s_branch .Lsc_done_pre
.Lsc_bwd_pre:
	v_add_u32_e32 v244, -3, v246
	v_lshlrev_b32_e32 v244, 10, v244
	v_lshl_add_u64 v[236:237], v[244:245], 0, v[48:49]
	v_add_u32_e32 v244, -11, v246
	v_lshlrev_b32_e32 v244, 10, v244
	v_lshl_add_u64 v[238:239], v[244:245], 0, v[48:49]
	v_add_u32_e32 v244, -7, v246
	v_lshlrev_b32_e32 v244, 9, v244
	v_lshl_add_u64 v[240:241], v[244:245], 0, v[44:45]
	v_lshlrev_b32_e32 v244, 9, v247
	v_lshl_add_u64 v[242:243], v[244:245], 0, v[50:51]
	global_load_dword v59, v[236:237], off offset:3072 sc0 sc1
	global_load_ushort v60, v[240:241], off offset:3584 sc0 sc1
	global_load_ushort v61, v[240:241], off offset:3840 sc0 sc1
	global_load_dword v62, v[236:237], off offset:2048 sc0 sc1
	global_load_ushort v63, v[240:241], off offset:3072 sc0 sc1
	global_load_ushort v64, v[240:241], off offset:3328 sc0 sc1
	global_load_dword v65, v[236:237], off offset:1024 sc0 sc1
	global_load_ushort v66, v[240:241], off offset:2560 sc0 sc1
	global_load_ushort v67, v[240:241], off offset:2816 sc0 sc1
	global_load_dword v68, v[236:237], off sc0 sc1
	global_load_ushort v69, v[240:241], off offset:2048 sc0 sc1
	global_load_ushort v70, v[240:241], off offset:2304 sc0 sc1
	global_load_dword v71, v[236:237], off offset:-1024 sc0 sc1
	global_load_ushort v72, v[240:241], off offset:1536 sc0 sc1
	global_load_ushort v73, v[240:241], off offset:1792 sc0 sc1
	global_load_dword v74, v[236:237], off offset:-2048 sc0 sc1
	global_load_ushort v75, v[240:241], off offset:1024 sc0 sc1
	global_load_ushort v76, v[240:241], off offset:1280 sc0 sc1
	global_load_dword v77, v[236:237], off offset:-3072 sc0 sc1
	global_load_ushort v78, v[240:241], off offset:512 sc0 sc1
	global_load_ushort v79, v[240:241], off offset:768 sc0 sc1
	global_load_dword v80, v[236:237], off offset:-4096 sc0 sc1
	global_load_ushort v81, v[240:241], off sc0 sc1
	global_load_ushort v82, v[240:241], off offset:256 sc0 sc1
	global_load_dword v83, v[238:239], off offset:3072 sc0 sc1
	global_load_ushort v84, v[240:241], off offset:-512 sc0 sc1
	global_load_ushort v85, v[240:241], off offset:-256 sc0 sc1
	global_load_dword v86, v[238:239], off offset:2048 sc0 sc1
	global_load_ushort v87, v[240:241], off offset:-1024 sc0 sc1
	global_load_ushort v88, v[240:241], off offset:-768 sc0 sc1
	global_load_dword v89, v[238:239], off offset:1024 sc0 sc1
	global_load_ushort v90, v[240:241], off offset:-1536 sc0 sc1
	global_load_ushort v91, v[240:241], off offset:-1280 sc0 sc1
	global_load_dword v92, v[238:239], off sc0 sc1
	global_load_ushort v93, v[240:241], off offset:-2048 sc0 sc1
	global_load_ushort v94, v[240:241], off offset:-1792 sc0 sc1
	global_load_dword v95, v[238:239], off offset:-1024 sc0 sc1
	global_load_ushort v96, v[240:241], off offset:-2560 sc0 sc1
	global_load_ushort v97, v[240:241], off offset:-2304 sc0 sc1
	global_load_dword v98, v[238:239], off offset:-2048 sc0 sc1
	global_load_ushort v99, v[240:241], off offset:-3072 sc0 sc1
	global_load_ushort v100, v[240:241], off offset:-2816 sc0 sc1
	global_load_dword v101, v[238:239], off offset:-3072 sc0 sc1
	global_load_ushort v102, v[240:241], off offset:-3584 sc0 sc1
	global_load_ushort v103, v[240:241], off offset:-3328 sc0 sc1
	global_load_dword v104, v[238:239], off offset:-4096 sc0 sc1
	global_load_ushort v105, v[240:241], off offset:-4096 sc0 sc1
	global_load_ushort v227, v[240:241], off offset:-3840 sc0 sc1
	global_load_ushort v228, v[242:243], off sc0 sc1
	global_load_ushort v229, v[242:243], off offset:-512 sc0 sc1
	global_load_ushort v230, v[242:243], off offset:-1024 sc0 sc1
	global_load_ushort v231, v[242:243], off offset:-1536 sc0 sc1
	global_load_ushort v232, v[242:243], off offset:-2048 sc0 sc1
	global_load_ushort v233, v[242:243], off offset:-2560 sc0 sc1
	global_load_ushort v234, v[242:243], off offset:-3072 sc0 sc1
	global_load_ushort v235, v[242:243], off offset:-3584 sc0 sc1
.Lsc_done_pre:
	s_waitcnt vmcnt(0)
	s_branch .LBB0_301

.LBB0_301:
	s_and_b64 s[2:3], s[26:27], exec
	s_cselect_b32 s33, s29, s31
	s_add_i32 s33, s33, s30
	s_waitcnt vmcnt(8)
	v_mov_b32_e32 v23, v59
	v_mov_b32_e32 v161, v60
	v_mov_b32_e32 v162, v61
	v_mov_b32_e32 v20, v62
	v_mov_b32_e32 v163, v63
	v_mov_b32_e32 v164, v64
	v_mov_b32_e32 v21, v65
	v_mov_b32_e32 v167, v66
	v_mov_b32_e32 v168, v67
	v_mov_b32_e32 v22, v68
	v_mov_b32_e32 v169, v69
	v_mov_b32_e32 v170, v70
	v_mov_b32_e32 v159, v71
	v_mov_b32_e32 v171, v72
	v_mov_b32_e32 v172, v73
	v_mov_b32_e32 v160, v74
	v_mov_b32_e32 v173, v75
	v_mov_b32_e32 v174, v76
	v_mov_b32_e32 v165, v77
	v_mov_b32_e32 v183, v78
	v_mov_b32_e32 v184, v79
	v_mov_b32_e32 v166, v80
	v_mov_b32_e32 v185, v81
	v_mov_b32_e32 v186, v82
	v_mov_b32_e32 v175, v83
	v_mov_b32_e32 v187, v84
	v_mov_b32_e32 v188, v85
	v_mov_b32_e32 v182, v86
	v_mov_b32_e32 v189, v87
	v_mov_b32_e32 v190, v88
	v_mov_b32_e32 v221, v89
	v_mov_b32_e32 v193, v90
	v_mov_b32_e32 v194, v91
	v_mov_b32_e32 v222, v92
	v_mov_b32_e32 v195, v93
	v_mov_b32_e32 v196, v94
	v_mov_b32_e32 v223, v95
	v_mov_b32_e32 v197, v96
	v_mov_b32_e32 v198, v97
	v_mov_b32_e32 v224, v98
	v_mov_b32_e32 v199, v99
	v_mov_b32_e32 v200, v100
	v_mov_b32_e32 v225, v101
	v_mov_b32_e32 v214, v102
	v_mov_b32_e32 v215, v103
	v_mov_b32_e32 v226, v104
	v_mov_b32_e32 v216, v105
	v_mov_b32_e32 v217, v227
	v_mov_b32_e32 v18, v228
	v_mov_b32_e32 v19, v229
	v_mov_b32_e32 v191, v230
	v_mov_b32_e32 v192, v231
	v_mov_b32_e32 v201, v232
	v_mov_b32_e32 v213, v233
	v_mov_b32_e32 v218, v234
	v_mov_b32_e32 v16, v235
	s_cmp_eq_u32 s31, 0
	s_cbranch_scc1 .Lsc_nopf
	s_add_i32 s2, s29, 64
	s_sub_i32 s3, s31, 64
	s_cmp_lg_u64 s[26:27], 0
	s_cselect_b32 s2, s2, s3
	s_add_i32 s2, s2, s30
	v_add_u32_e32 v246, s2, v133
	v_mov_b32_e32 v245, 0
	v_add_u32_e32 v247, s2, v149
	s_cmp_lg_u64 s[26:27], 0
	s_cbranch_scc0 .Lsc_bwd_lp
	v_add_u32_e32 v244, 4, v246
	v_lshlrev_b32_e32 v244, 10, v244
	v_lshl_add_u64 v[236:237], v[244:245], 0, v[48:49]
	v_add_u32_e32 v244, 12, v246
	v_lshlrev_b32_e32 v244, 10, v244
	v_lshl_add_u64 v[238:239], v[244:245], 0, v[48:49]
	v_add_u32_e32 v244, 8, v246
	v_lshlrev_b32_e32 v244, 9, v244
	v_lshl_add_u64 v[240:241], v[244:245], 0, v[44:45]
	v_lshlrev_b32_e32 v244, 9, v247
	v_lshl_add_u64 v[242:243], v[244:245], 0, v[50:51]
	global_load_dword v59, v[236:237], off offset:-4096 sc0 sc1
	global_load_ushort v60, v[240:241], off offset:-4096 sc0 sc1
	global_load_ushort v61, v[240:241], off offset:-3840 sc0 sc1
	global_load_dword v62, v[236:237], off offset:-3072 sc0 sc1
	global_load_ushort v63, v[240:241], off offset:-3584 sc0 sc1
	global_load_ushort v64, v[240:241], off offset:-3328 sc0 sc1
	global_load_dword v65, v[236:237], off offset:-2048 sc0 sc1
	global_load_ushort v66, v[240:241], off offset:-3072 sc0 sc1
	global_load_ushort v67, v[240:241], off offset:-2816 sc0 sc1
	global_load_dword v68, v[236:237], off offset:-1024 sc0 sc1
	global_load_ushort v69, v[240:241], off offset:-2560 sc0 sc1
	global_load_ushort v70, v[240:241], off offset:-2304 sc0 sc1
	global_load_dword v71, v[236:237], off sc0 sc1
	global_load_ushort v72, v[240:241], off offset:-2048 sc0 sc1
	global_load_ushort v73, v[240:241], off offset:-1792 sc0 sc1
	global_load_dword v74, v[236:237], off offset:1024 sc0 sc1
	global_load_ushort v75, v[240:241], off offset:-1536 sc0 sc1
	global_load_ushort v76, v[240:241], off offset:-1280 sc0 sc1
	global_load_dword v77, v[236:237], off offset:2048 sc0 sc1
	global_load_ushort v78, v[240:241], off offset:-1024 sc0 sc1
	global_load_ushort v79, v[240:241], off offset:-768 sc0 sc1
	global_load_dword v80, v[236:237], off offset:3072 sc0 sc1
	global_load_ushort v81, v[240:241], off offset:-512 sc0 sc1
	global_load_ushort v82, v[240:241], off offset:-256 sc0 sc1
	global_load_dword v83, v[238:239], off offset:-4096 sc0 sc1
	global_load_ushort v84, v[240:241], off sc0 sc1
	global_load_ushort v85, v[240:241], off offset:256 sc0 sc1
	global_load_dword v86, v[238:239], off offset:-3072 sc0 sc1
	global_load_ushort v87, v[240:241], off offset:512 sc0 sc1
	global_load_ushort v88, v[240:241], off offset:768 sc0 sc1
	global_load_dword v89, v[238:239], off offset:-2048 sc0 sc1
	global_load_ushort v90, v[240:241], off offset:1024 sc0 sc1
	global_load_ushort v91, v[240:241], off offset:1280 sc0 sc1
	global_load_dword v92, v[238:239], off offset:-1024 sc0 sc1
	global_load_ushort v93, v[240:241], off offset:1536 sc0 sc1
	global_load_ushort v94, v[240:241], off offset:1792 sc0 sc1
	global_load_dword v95, v[238:239], off sc0 sc1
	global_load_ushort v96, v[240:241], off offset:2048 sc0 sc1
	global_load_ushort v97, v[240:241], off offset:2304 sc0 sc1
	global_load_dword v98, v[238:239], off offset:1024 sc0 sc1
	global_load_ushort v99, v[240:241], off offset:2560 sc0 sc1
	global_load_ushort v100, v[240:241], off offset:2816 sc0 sc1
	global_load_dword v101, v[238:239], off offset:2048 sc0 sc1
	global_load_ushort v102, v[240:241], off offset:3072 sc0 sc1
	global_load_ushort v103, v[240:241], off offset:3328 sc0 sc1
	global_load_dword v104, v[238:239], off offset:3072 sc0 sc1
	global_load_ushort v105, v[240:241], off offset:3584 sc0 sc1
	global_load_ushort v227, v[240:241], off offset:3840 sc0 sc1
	global_load_ushort v228, v[242:243], off sc0 sc1
	global_load_ushort v229, v[242:243], off offset:512 sc0 sc1
	global_load_ushort v230, v[242:243], off offset:1024 sc0 sc1
	global_load_ushort v231, v[242:243], off offset:1536 sc0 sc1
	global_load_ushort v232, v[242:243], off offset:2048 sc0 sc1
	global_load_ushort v233, v[242:243], off offset:2560 sc0 sc1
	global_load_ushort v234, v[242:243], off offset:3072 sc0 sc1
	global_load_ushort v235, v[242:243], off offset:3584 sc0 sc1
	s_branch .Lsc_done_lp

.Lsc_done_lp:
.Lsc_nopf:
	v_add_f32_e32 v220, v23, v20
	v_lshlrev_b32_e32 v17, 16, v18
	v_lshlrev_b32_e32 v18, 16, v19
	v_lshlrev_b32_e32 v19, 16, v191
	v_lshlrev_b32_e32 v191, 16, v192
	v_lshlrev_b32_e32 v192, 16, v201
	v_lshlrev_b32_e32 v201, 16, v213
	v_lshlrev_b32_e32 v213, 16, v218
	v_lshlrev_b32_e32 v218, 16, v16
	v_cvt_pk_bf16_f32 v16, v17, v18
	v_cvt_pk_bf16_f32 v17, v19, v191
	v_cvt_pk_bf16_f32 v18, v192, v201
	v_cvt_pk_bf16_f32 v19, v213, v218
	v_add_f32_e32 v218, v220, v21
	v_add_f32_e32 v219, v218, v22
	v_add_f32_e32 v201, v219, v159
	v_add_f32_e32 v213, v201, v160
	v_add_f32_e32 v191, v213, v165
	v_add_f32_e32 v192, v191, v166
	v_add_f32_e32 v175, v192, v175
	v_add_f32_e32 v182, v175, v182
	v_add_f32_e32 v165, v182, v221
	v_add_f32_e32 v166, v165, v222
	v_add_f32_e32 v159, v166, v223
	v_add_f32_e32 v160, v159, v224
	v_add_f32_e32 v21, v160, v225
	v_add_f32_e32 v22, v21, v226
	ds_write_b32 v56, v22
	ds_write_b128 v124, v[16:19] offset:53248
	s_waitcnt lgkmcnt(0)
	s_barrier
	ds_read2st64_b32 v[18:19], v57 offset1:2
	ds_read2st64_b32 v[16:17], v57 offset0:4 offset1:6
	s_waitcnt lgkmcnt(1)
	v_add_f32_e32 v18, 0, v18
	v_add_f32_e32 v20, v18, v19
	s_waitcnt lgkmcnt(0)
	v_add_f32_e32 v20, v20, v16
	v_add_f32_e32 v20, v20, v17
	v_mul_f32_e32 v20, 0x3fb8aa3b, v20
	v_exp_f32_e32 v20, v20
	s_and_saveexec_b64 s[2:3], vcc
	s_cbranch_execz .LBB0_300
	ds_write_b32 v58, v20
	s_branch .LBB0_300

.LBB0_309:
	s_ashr_i32 s20, s18, 3
	s_and_b32 s19, s18, 3
	s_bfe_u32 s21, s18, 0x10002
	s_cmp_eq_u32 s21, 0
	s_cselect_b64 s[14:15], -1, 0
	s_lshl_b32 s94, s21, 9
	v_lshl_add_u64 v[38:39], v[20:21], 0, s[94:95]
	s_lshl_b32 s94, s19, 7
	v_mov_b32_e32 v96, 0
	s_mov_b32 s23, 0
	s_lshl_b32 s24, s20, 10
	s_lshl_b32 s22, s19, 6
	v_cndmask_b32_e64 v37, v25, v42, s[14:15]
	v_cndmask_b32_e64 v97, v48, v47, s[14:15]
	v_cndmask_b32_e64 v98, v50, v49, s[14:15]
	v_cndmask_b32_e64 v99, v52, v51, s[14:15]
	v_cndmask_b32_e64 v100, v54, v53, s[14:15]
	v_cndmask_b32_e64 v101, v56, v55, s[14:15]
	v_cndmask_b32_e64 v102, v58, v57, s[14:15]
	v_cndmask_b32_e64 v103, v60, v59, s[14:15]
	v_cndmask_b32_e64 v104, v62, v61, s[14:15]
	v_cndmask_b32_e64 v105, v64, v63, s[14:15]
	v_cndmask_b32_e64 v106, v66, v65, s[14:15]
	v_cndmask_b32_e64 v107, v68, v67, s[14:15]
	v_cndmask_b32_e64 v108, v70, v69, s[14:15]
	v_cndmask_b32_e64 v109, v72, v71, s[14:15]
	v_cndmask_b32_e64 v110, v74, v73, s[14:15]
	v_cndmask_b32_e64 v111, v76, v75, s[14:15]
	v_cndmask_b32_e64 v112, v77, v43, s[14:15]
	v_cndmask_b32_e64 v113, v79, v78, s[14:15]
	v_cndmask_b32_e64 v114, v81, v80, s[14:15]
	v_cndmask_b32_e64 v115, v83, v82, s[14:15]
	v_cndmask_b32_e64 v116, v85, v84, s[14:15]
	s_movk_i32 s25, 0x3c0
	v_mov_b32_e32 v0, 0
	v_mov_b32_e32 v1, v96
	v_mov_b32_e32 v2, v96
	v_mov_b32_e32 v3, v96
	v_mov_b32_e32 v4, 0
	v_mov_b32_e32 v5, v96
	v_mov_b32_e32 v6, v96
	v_mov_b32_e32 v7, v96
	v_mov_b32_e32 v8, 0
	v_mov_b32_e32 v9, v96
	v_mov_b32_e32 v10, v96
	v_mov_b32_e32 v11, v96
	v_mov_b32_e32 v12, 0
	v_mov_b32_e32 v13, v96
	v_mov_b32_e32 v14, v96
	v_mov_b32_e32 v15, v96
	v_cndmask_b32_e64 v117, v87, v86, s[14:15]
	v_cndmask_b32_e64 v118, v89, v88, s[14:15]
	v_cndmask_b32_e64 v119, v91, v90, s[14:15]
	v_lshl_add_u64 v[40:41], v[22:23], 0, s[94:95]
	s_mov_b32 s26, 0xc988000
	s_and_b64 s[2:3], s[14:15], exec
	s_cselect_b32 s2, s23, s25
	s_add_i32 s2, s2, s24
	v_add_u32_e32 v246, s2, v37
	v_mov_b32_e32 v245, 0
	v_add_u32_e32 v247, s2, v112
	v_lshl_add_u64 v[240:241], s[46:47], 0, v[176:177]
	v_add_co_u32_e64 v240, s[16:17], s26, v240
	s_nop 1
	v_addc_co_u32_e64 v241, s[16:17], 0, v241, s[16:17]
	s_cmp_lg_u64 s[14:15], 0
	s_cbranch_scc0 .Lsa_bwd_pre
	v_add_u32_e32 v244, 4, v246
	v_lshlrev_b32_e32 v244, 10, v244
	v_lshl_add_u64 v[236:237], v[244:245], 0, v[38:39]
	v_add_u32_e32 v244, 12, v246
	v_lshlrev_b32_e32 v244, 10, v244
	v_lshl_add_u64 v[238:239], v[244:245], 0, v[38:39]
	v_add_u32_e32 v244, 8, v246
	v_lshlrev_b32_e32 v244, 9, v244
	v_lshl_add_u64 v[240:241], v[244:245], 0, v[240:241]
	v_lshlrev_b32_e32 v244, 9, v247
	v_lshl_add_u64 v[242:243], v[244:245], 0, v[40:41]
	global_load_dword v159, v[236:237], off offset:-4096 sc0 sc1
	global_load_ushort v160, v[240:241], off offset:-3840 sc0 sc1
	global_load_dword v161, v[236:237], off offset:-3072 sc0 sc1
	global_load_ushort v162, v[240:241], off offset:-3328 sc0 sc1
	global_load_dword v163, v[236:237], off offset:-2048 sc0 sc1
	global_load_ushort v164, v[240:241], off offset:-2816 sc0 sc1
	global_load_dword v165, v[236:237], off offset:-1024 sc0 sc1
	global_load_ushort v166, v[240:241], off offset:-2304 sc0 sc1
	global_load_dword v167, v[236:237], off sc0 sc1
	global_load_ushort v168, v[240:241], off offset:-1792 sc0 sc1
	global_load_dword v169, v[236:237], off offset:1024 sc0 sc1
	global_load_ushort v170, v[240:241], off offset:-1280 sc0 sc1
	global_load_dword v171, v[236:237], off offset:2048 sc0 sc1
	global_load_ushort v172, v[240:241], off offset:-768 sc0 sc1
	global_load_dword v173, v[236:237], off offset:3072 sc0 sc1
	global_load_ushort v174, v[240:241], off offset:-256 sc0 sc1
	global_load_dword v175, v[238:239], off offset:-4096 sc0 sc1
	global_load_ushort v182, v[240:241], off offset:256 sc0 sc1
	global_load_dword v183, v[238:239], off offset:-3072 sc0 sc1
	global_load_ushort v184, v[240:241], off offset:768 sc0 sc1
	global_load_dword v185, v[238:239], off offset:-2048 sc0 sc1
	global_load_ushort v186, v[240:241], off offset:1280 sc0 sc1
	global_load_dword v187, v[238:239], off offset:-1024 sc0 sc1
	global_load_ushort v188, v[240:241], off offset:1792 sc0 sc1
	global_load_dword v189, v[238:239], off sc0 sc1
	global_load_ushort v190, v[240:241], off offset:2304 sc0 sc1
	global_load_dword v191, v[238:239], off offset:1024 sc0 sc1
	global_load_ushort v192, v[240:241], off offset:2816 sc0 sc1
	global_load_dword v193, v[238:239], off offset:2048 sc0 sc1
	global_load_ushort v194, v[240:241], off offset:3328 sc0 sc1
	global_load_dword v195, v[238:239], off offset:3072 sc0 sc1
	global_load_ushort v196, v[240:241], off offset:3840 sc0 sc1
	global_load_ushort v197, v[242:243], off sc0 sc1
	global_load_ushort v198, v[242:243], off offset:512 sc0 sc1
	global_load_ushort v199, v[242:243], off offset:1024 sc0 sc1
	global_load_ushort v200, v[242:243], off offset:1536 sc0 sc1
	global_load_ushort v201, v[242:243], off offset:2048 sc0 sc1
	global_load_ushort v213, v[242:243], off offset:2560 sc0 sc1
	global_load_ushort v214, v[242:243], off offset:3072 sc0 sc1
	global_load_ushort v215, v[242:243], off offset:3584 sc0 sc1
	s_branch .Lsa_done_pre
.Lsa_bwd_pre:
	v_add_u32_e32 v244, -3, v246
	v_lshlrev_b32_e32 v244, 10, v244
	v_lshl_add_u64 v[236:237], v[244:245], 0, v[38:39]
	v_add_u32_e32 v244, -11, v246
	v_lshlrev_b32_e32 v244, 10, v244
	v_lshl_add_u64 v[238:239], v[244:245], 0, v[38:39]
	v_add_u32_e32 v244, -7, v246
	v_lshlrev_b32_e32 v244, 9, v244
	v_lshl_add_u64 v[240:241], v[244:245], 0, v[240:241]
	v_lshlrev_b32_e32 v244, 9, v247
	v_lshl_add_u64 v[242:243], v[244:245], 0, v[40:41]
	global_load_dword v159, v[236:237], off offset:3072 sc0 sc1
	global_load_ushort v160, v[240:241], off offset:3840 sc0 sc1
	global_load_dword v161, v[236:237], off offset:2048 sc0 sc1
	global_load_ushort v162, v[240:241], off offset:3328 sc0 sc1
	global_load_dword v163, v[236:237], off offset:1024 sc0 sc1
	global_load_ushort v164, v[240:241], off offset:2816 sc0 sc1
	global_load_dword v165, v[236:237], off sc0 sc1
	global_load_ushort v166, v[240:241], off offset:2304 sc0 sc1
	global_load_dword v167, v[236:237], off offset:-1024 sc0 sc1
	global_load_ushort v168, v[240:241], off offset:1792 sc0 sc1
	global_load_dword v169, v[236:237], off offset:-2048 sc0 sc1
	global_load_ushort v170, v[240:241], off offset:1280 sc0 sc1
	global_load_dword v171, v[236:237], off offset:-3072 sc0 sc1
	global_load_ushort v172, v[240:241], off offset:768 sc0 sc1
	global_load_dword v173, v[236:237], off offset:-4096 sc0 sc1
	global_load_ushort v174, v[240:241], off offset:256 sc0 sc1
	global_load_dword v175, v[238:239], off offset:3072 sc0 sc1
	global_load_ushort v182, v[240:241], off offset:-256 sc0 sc1
	global_load_dword v183, v[238:239], off offset:2048 sc0 sc1
	global_load_ushort v184, v[240:241], off offset:-768 sc0 sc1
	global_load_dword v185, v[238:239], off offset:1024 sc0 sc1
	global_load_ushort v186, v[240:241], off offset:-1280 sc0 sc1
	global_load_dword v187, v[238:239], off sc0 sc1
	global_load_ushort v188, v[240:241], off offset:-1792 sc0 sc1
	global_load_dword v189, v[238:239], off offset:-1024 sc0 sc1
	global_load_ushort v190, v[240:241], off offset:-2304 sc0 sc1
	global_load_dword v191, v[238:239], off offset:-2048 sc0 sc1
	global_load_ushort v192, v[240:241], off offset:-2816 sc0 sc1
	global_load_dword v193, v[238:239], off offset:-3072 sc0 sc1
	global_load_ushort v194, v[240:241], off offset:-3328 sc0 sc1
	global_load_dword v195, v[238:239], off offset:-4096 sc0 sc1
	global_load_ushort v196, v[240:241], off offset:-3840 sc0 sc1
	global_load_ushort v197, v[242:243], off sc0 sc1
	global_load_ushort v198, v[242:243], off offset:-512 sc0 sc1
	global_load_ushort v199, v[242:243], off offset:-1024 sc0 sc1
	global_load_ushort v200, v[242:243], off offset:-1536 sc0 sc1
	global_load_ushort v201, v[242:243], off offset:-2048 sc0 sc1
	global_load_ushort v213, v[242:243], off offset:-2560 sc0 sc1
	global_load_ushort v214, v[242:243], off offset:-3072 sc0 sc1
	global_load_ushort v215, v[242:243], off offset:-3584 sc0 sc1
.Lsa_done_pre:
	s_branch .LBB0_311
.LBB0_310:
	s_or_b64 exec, exec, s[2:3]
	v_cndmask_b32_e64 v18, 0, v18, s[6:7]
	v_add_f32_e32 v19, v19, v18
	v_cndmask_b32_e64 v18, v18, v19, s[8:9]
	v_add_f32_e32 v16, v16, v18
	v_cndmask_b32_e64 v16, v18, v16, s[10:11]
	v_add_f32_e32 v17, v17, v16
	v_cndmask_b32_e64 v153, v16, v17, s[12:13]
	v_add_f32_e32 v16, v153, v120
	v_add_f32_e32 v17, v152, v153
	v_sub_f32_e32 v16, v127, v16
	v_sub_f32_e32 v17, v127, v17
	v_mul_f32_e32 v16, 0x3fb8aa3b, v16
	v_mul_f32_e32 v17, 0x3fb8aa3b, v17
	v_exp_f32_e32 v16, v16
	v_exp_f32_e32 v17, v17
	v_lshlrev_b32_e32 v121, 16, v121
	v_lshlrev_b32_e32 v122, 16, v122
	v_mul_f32_e32 v16, v16, v121
	v_mul_f32_e32 v17, v17, v122
	v_cvt_pk_bf16_f32 v16, v16, v17
	v_add_f32_e32 v17, v150, v153
	v_add_f32_e32 v18, v151, v153
	v_sub_f32_e32 v17, v127, v17
	v_sub_f32_e32 v18, v127, v18
	v_mul_f32_e32 v17, 0x3fb8aa3b, v17
	v_mul_f32_e32 v18, 0x3fb8aa3b, v18
	v_exp_f32_e32 v17, v17
	v_exp_f32_e32 v18, v18
	v_lshlrev_b32_e32 v123, 16, v123
	v_lshlrev_b32_e32 v126, 16, v126
	v_mul_f32_e32 v17, v17, v123
	v_mul_f32_e32 v18, v18, v126
	v_cvt_pk_bf16_f32 v17, v17, v18
	v_add_f32_e32 v18, v147, v153
	v_add_f32_e32 v19, v148, v153
	v_sub_f32_e32 v18, v127, v18
	v_sub_f32_e32 v19, v127, v19
	v_mul_f32_e32 v18, 0x3fb8aa3b, v18
	v_mul_f32_e32 v19, 0x3fb8aa3b, v19
	v_exp_f32_e32 v18, v18
	v_exp_f32_e32 v19, v19
	v_lshlrev_b32_e32 v128, 16, v128
	v_lshlrev_b32_e32 v131, 16, v131
	v_mul_f32_e32 v18, v18, v128
	v_mul_f32_e32 v19, v19, v131
	v_cvt_pk_bf16_f32 v18, v18, v19
	v_add_f32_e32 v19, v143, v153
	v_add_f32_e32 v120, v144, v153
	v_sub_f32_e32 v19, v127, v19
	v_sub_f32_e32 v120, v127, v120
	v_mul_f32_e32 v19, 0x3fb8aa3b, v19
	v_mul_f32_e32 v120, 0x3fb8aa3b, v120
	v_exp_f32_e32 v19, v19
	v_exp_f32_e32 v120, v120
	v_lshlrev_b32_e32 v132, 16, v132
	v_lshlrev_b32_e32 v133, 16, v133
	v_mul_f32_e32 v19, v19, v132
	v_mul_f32_e32 v120, v120, v133
	v_cvt_pk_bf16_f32 v19, v19, v120
	v_add_f32_e32 v120, v138, v153
	v_add_f32_e32 v121, v139, v153
	v_sub_f32_e32 v120, v127, v120
	v_sub_f32_e32 v121, v127, v121
	v_mul_f32_e32 v120, 0x3fb8aa3b, v120
	v_mul_f32_e32 v121, 0x3fb8aa3b, v121
	v_exp_f32_e32 v120, v120
	v_exp_f32_e32 v121, v121
	v_lshlrev_b32_e32 v136, 16, v136
	v_lshlrev_b32_e32 v137, 16, v137
	v_mul_f32_e32 v120, v120, v136
	v_mul_f32_e32 v121, v121, v137
	v_cvt_pk_bf16_f32 v120, v120, v121
	v_add_f32_e32 v121, v134, v153
	v_add_f32_e32 v122, v135, v153
	v_sub_f32_e32 v121, v127, v121
	v_sub_f32_e32 v122, v127, v122
	v_mul_f32_e32 v121, 0x3fb8aa3b, v121
	v_mul_f32_e32 v122, 0x3fb8aa3b, v122
	v_exp_f32_e32 v121, v121
	v_exp_f32_e32 v122, v122
	v_lshlrev_b32_e32 v140, 16, v140
	v_lshlrev_b32_e32 v141, 16, v141
	v_mul_f32_e32 v121, v121, v140
	v_mul_f32_e32 v122, v122, v141
	v_cvt_pk_bf16_f32 v121, v121, v122
	v_add_f32_e32 v122, v129, v153
	v_add_f32_e32 v123, v130, v153
	v_sub_f32_e32 v122, v127, v122
	v_sub_f32_e32 v123, v127, v123
	v_mul_f32_e32 v122, 0x3fb8aa3b, v122
	v_mul_f32_e32 v123, 0x3fb8aa3b, v123
	v_exp_f32_e32 v122, v122
	v_exp_f32_e32 v123, v123
	v_lshlrev_b32_e32 v142, 16, v142
	v_lshlrev_b32_e32 v145, 16, v145
	v_mul_f32_e32 v122, v122, v142
	v_mul_f32_e32 v123, v123, v145
	v_cvt_pk_bf16_f32 v122, v122, v123
	v_add_f32_e32 v123, v124, v153
	v_add_f32_e32 v124, v125, v153
	v_sub_f32_e32 v123, v127, v123
	v_mul_f32_e32 v123, 0x3fb8aa3b, v123
	v_sub_f32_e32 v124, v127, v124
	v_exp_f32_e32 v123, v123
	v_mul_f32_e32 v124, 0x3fb8aa3b, v124
	v_exp_f32_e32 v124, v124
	v_lshlrev_b32_e32 v146, 16, v146
	v_lshlrev_b32_e32 v149, 16, v149
	v_mul_f32_e32 v123, v123, v146
	v_mul_f32_e32 v124, v124, v149
	v_cvt_pk_bf16_f32 v123, v123, v124
	ds_write_b128 v93, v[16:19] offset:34816
	ds_write_b128 v93, v[120:123] offset:34832
	s_waitcnt lgkmcnt(0)
	s_barrier
	ds_read_b128 v[16:19], v95
	s_sub_i32 s25, s25, 64
	s_add_i32 s23, s23, 64
	s_cmpk_eq_i32 s25, 0xffc0
	s_waitcnt lgkmcnt(0)
	v_pk_mul_f32 v[0:1], v[0:1], v[16:17]
	v_pk_mul_f32 v[2:3], v[2:3], v[18:19]
	v_pk_mul_f32 v[4:5], v[4:5], v[16:17]
	v_pk_mul_f32 v[6:7], v[6:7], v[18:19]
	v_pk_mul_f32 v[8:9], v[8:9], v[16:17]
	v_pk_mul_f32 v[10:11], v[10:11], v[18:19]
	v_pk_mul_f32 v[12:13], v[12:13], v[16:17]
	v_pk_mul_f32 v[14:15], v[14:15], v[18:19]
	ds_read_b128 v[16:19], v24 offset:34816
	ds_read_b128 v[120:123], v94 offset:53248
	s_waitcnt lgkmcnt(0)
	v_mfma_f32_16x16x32_bf16 v[0:3], v[16:19], v[120:123], v[0:3]
	ds_read_b128 v[120:123], v94 offset:55552
	s_waitcnt lgkmcnt(0)
	v_mfma_f32_16x16x32_bf16 v[4:7], v[16:19], v[120:123], v[4:7]
	ds_read_b128 v[120:123], v94 offset:57856
	s_waitcnt lgkmcnt(0)
	v_mfma_f32_16x16x32_bf16 v[8:11], v[16:19], v[120:123], v[8:11]
	ds_read_b128 v[120:123], v94 offset:60160
	s_waitcnt lgkmcnt(0)
	v_mfma_f32_16x16x32_bf16 v[12:15], v[16:19], v[120:123], v[12:15]
	ds_read_b128 v[16:19], v24 offset:34880
	ds_read_b128 v[120:123], v94 offset:53312
	s_waitcnt lgkmcnt(0)
	v_mfma_f32_16x16x32_bf16 v[0:3], v[16:19], v[120:123], v[0:3]
	ds_read_b128 v[120:123], v94 offset:55616
	s_waitcnt lgkmcnt(0)
	v_mfma_f32_16x16x32_bf16 v[4:7], v[16:19], v[120:123], v[4:7]
	ds_read_b128 v[120:123], v94 offset:57920
	s_waitcnt lgkmcnt(0)
	v_mfma_f32_16x16x32_bf16 v[8:11], v[16:19], v[120:123], v[8:11]
	ds_read_b128 v[120:123], v94 offset:60224
	s_waitcnt lgkmcnt(0)
	s_barrier
	v_mfma_f32_16x16x32_bf16 v[12:15], v[16:19], v[120:123], v[12:15]
	s_cbranch_scc1 .LBB0_313
.LBB0_311:
	s_waitcnt vmcnt(0)
	v_mov_b32_e32 v120, v159
	v_mov_b32_e32 v121, v160
	v_mov_b32_e32 v124, v161
	v_mov_b32_e32 v122, v162
	v_mov_b32_e32 v125, v163
	v_mov_b32_e32 v123, v164
	v_mov_b32_e32 v127, v165
	v_mov_b32_e32 v126, v166
	v_mov_b32_e32 v129, v167
	v_mov_b32_e32 v128, v168
	v_mov_b32_e32 v130, v169
	v_mov_b32_e32 v131, v170
	v_mov_b32_e32 v134, v171
	v_mov_b32_e32 v132, v172
	v_mov_b32_e32 v135, v173
	v_mov_b32_e32 v133, v174
	v_mov_b32_e32 v138, v175
	v_mov_b32_e32 v136, v182
	v_mov_b32_e32 v139, v183
	v_mov_b32_e32 v137, v184
	v_mov_b32_e32 v153, v185
	v_mov_b32_e32 v140, v186
	v_mov_b32_e32 v154, v187
	v_mov_b32_e32 v141, v188
	v_mov_b32_e32 v155, v189
	v_mov_b32_e32 v142, v190
	v_mov_b32_e32 v156, v191
	v_mov_b32_e32 v145, v192
	v_mov_b32_e32 v157, v193
	v_mov_b32_e32 v146, v194
	v_mov_b32_e32 v158, v195
	v_mov_b32_e32 v149, v196
	v_mov_b32_e32 v18, v197
	v_mov_b32_e32 v19, v198
	v_mov_b32_e32 v143, v199
	v_mov_b32_e32 v144, v200
	v_mov_b32_e32 v147, v201
	v_mov_b32_e32 v148, v213
	v_mov_b32_e32 v150, v214
	v_mov_b32_e32 v16, v215
	s_cmp_eq_u32 s25, 0
	s_cbranch_scc1 .Lsa_nopf
	s_add_i32 s16, s23, 64
	s_sub_i32 s17, s25, 64
	s_and_b64 s[2:3], s[14:15], exec
	s_cselect_b32 s2, s16, s17
	s_add_i32 s2, s2, s24
	v_add_u32_e32 v246, s2, v37
	v_mov_b32_e32 v245, 0
	v_add_u32_e32 v247, s2, v112
	v_lshl_add_u64 v[240:241], s[46:47], 0, v[176:177]
	v_add_co_u32_e64 v240, s[16:17], s26, v240
	s_nop 1
	v_addc_co_u32_e64 v241, s[16:17], 0, v241, s[16:17]
	s_cmp_lg_u64 s[14:15], 0
	s_cbranch_scc0 .Lsa_bwd_lp
	v_add_u32_e32 v244, 4, v246
	v_lshlrev_b32_e32 v244, 10, v244
	v_lshl_add_u64 v[236:237], v[244:245], 0, v[38:39]
	v_add_u32_e32 v244, 12, v246
	v_lshlrev_b32_e32 v244, 10, v244
	v_lshl_add_u64 v[238:239], v[244:245], 0, v[38:39]
	v_add_u32_e32 v244, 8, v246
	v_lshlrev_b32_e32 v244, 9, v244
	v_lshl_add_u64 v[240:241], v[244:245], 0, v[240:241]
	v_lshlrev_b32_e32 v244, 9, v247
	v_lshl_add_u64 v[242:243], v[244:245], 0, v[40:41]
	global_load_dword v159, v[236:237], off offset:-4096 sc0 sc1
	global_load_ushort v160, v[240:241], off offset:-3840 sc0 sc1
	global_load_dword v161, v[236:237], off offset:-3072 sc0 sc1
	global_load_ushort v162, v[240:241], off offset:-3328 sc0 sc1
	global_load_dword v163, v[236:237], off offset:-2048 sc0 sc1
	global_load_ushort v164, v[240:241], off offset:-2816 sc0 sc1
	global_load_dword v165, v[236:237], off offset:-1024 sc0 sc1
	global_load_ushort v166, v[240:241], off offset:-2304 sc0 sc1
	global_load_dword v167, v[236:237], off sc0 sc1
	global_load_ushort v168, v[240:241], off offset:-1792 sc0 sc1
	global_load_dword v169, v[236:237], off offset:1024 sc0 sc1
	global_load_ushort v170, v[240:241], off offset:-1280 sc0 sc1
	global_load_dword v171, v[236:237], off offset:2048 sc0 sc1
	global_load_ushort v172, v[240:241], off offset:-768 sc0 sc1
	global_load_dword v173, v[236:237], off offset:3072 sc0 sc1
	global_load_ushort v174, v[240:241], off offset:-256 sc0 sc1
	global_load_dword v175, v[238:239], off offset:-4096 sc0 sc1
	global_load_ushort v182, v[240:241], off offset:256 sc0 sc1
	global_load_dword v183, v[238:239], off offset:-3072 sc0 sc1
	global_load_ushort v184, v[240:241], off offset:768 sc0 sc1
	global_load_dword v185, v[238:239], off offset:-2048 sc0 sc1
	global_load_ushort v186, v[240:241], off offset:1280 sc0 sc1
	global_load_dword v187, v[238:239], off offset:-1024 sc0 sc1
	global_load_ushort v188, v[240:241], off offset:1792 sc0 sc1
	global_load_dword v189, v[238:239], off sc0 sc1
	global_load_ushort v190, v[240:241], off offset:2304 sc0 sc1
	global_load_dword v191, v[238:239], off offset:1024 sc0 sc1
	global_load_ushort v192, v[240:241], off offset:2816 sc0 sc1
	global_load_dword v193, v[238:239], off offset:2048 sc0 sc1
	global_load_ushort v194, v[240:241], off offset:3328 sc0 sc1
	global_load_dword v195, v[238:239], off offset:3072 sc0 sc1
	global_load_ushort v196, v[240:241], off offset:3840 sc0 sc1
	global_load_ushort v197, v[242:243], off sc0 sc1
	global_load_ushort v198, v[242:243], off offset:512 sc0 sc1
	global_load_ushort v199, v[242:243], off offset:1024 sc0 sc1
	global_load_ushort v200, v[242:243], off offset:1536 sc0 sc1
	global_load_ushort v201, v[242:243], off offset:2048 sc0 sc1
	global_load_ushort v213, v[242:243], off offset:2560 sc0 sc1
	global_load_ushort v214, v[242:243], off offset:3072 sc0 sc1
	global_load_ushort v215, v[242:243], off offset:3584 sc0 sc1
	s_branch .Lsa_done_lp

.Lsa_done_lp:
.Lsa_nopf:
	v_add_f32_e32 v152, v120, v124
	v_lshlrev_b32_e32 v17, 16, v18
	v_lshlrev_b32_e32 v18, 16, v19
	v_lshlrev_b32_e32 v19, 16, v143
	v_lshlrev_b32_e32 v143, 16, v144
	v_lshlrev_b32_e32 v144, 16, v147
	v_lshlrev_b32_e32 v147, 16, v148
	v_lshlrev_b32_e32 v148, 16, v150
	v_lshlrev_b32_e32 v150, 16, v16
	v_cvt_pk_bf16_f32 v16, v17, v18
	v_cvt_pk_bf16_f32 v17, v19, v143
	v_cvt_pk_bf16_f32 v18, v144, v147
	v_cvt_pk_bf16_f32 v19, v148, v150
	v_add_f32_e32 v150, v152, v125
	v_add_f32_e32 v151, v150, v127
	v_add_f32_e32 v147, v151, v129
	v_add_f32_e32 v148, v147, v130
	v_add_f32_e32 v143, v148, v134
	v_add_f32_e32 v144, v143, v135
	v_add_f32_e32 v138, v144, v138
	v_add_f32_e32 v139, v138, v139
	v_add_f32_e32 v134, v139, v153
	v_add_f32_e32 v135, v134, v154
	v_add_f32_e32 v129, v135, v155
	v_add_f32_e32 v130, v129, v156
	v_add_f32_e32 v124, v130, v157
	v_add_f32_e32 v125, v124, v158
	ds_write_b32 v44, v125
	ds_write_b128 v92, v[16:19] offset:53248
	s_waitcnt lgkmcnt(0)
	s_barrier
	ds_read2st64_b32 v[18:19], v45 offset1:2
	ds_read2st64_b32 v[16:17], v45 offset0:4 offset1:6
	s_waitcnt lgkmcnt(1)
	v_add_f32_e32 v18, 0, v18
	v_add_f32_e32 v127, v18, v19
	s_waitcnt lgkmcnt(0)
	v_add_f32_e32 v127, v127, v16
	v_add_f32_e32 v127, v127, v17
	s_and_saveexec_b64 s[2:3], vcc
	s_cbranch_execz .LBB0_310
	v_mul_f32_e32 v153, 0x3fb8aa3b, v127
	v_exp_f32_e32 v153, v153
	v_add_f32_e32 v96, v96, v127
	ds_write_b32 v46, v153
	s_branch .LBB0_310
